# DSA collect fast path with exec-masked batched returning atomics
# speedup vs baseline: 1.0095x; 1.0095x over previous
; __device__ __forceinline__ void dsa_item(const KP& p, int b, int tile, char* smem) {
;     ...
;     for (int kt = wid; kt < nkt; kt += 4) {
;       h8 ca[2];
; #pragma unroll
;       for (int i = 0; i < 2; ++i) ca[i] = na[i];
;       loadk(kt + 4 < nkt ? kt + 4 : kt, na);
;       float sc[8];
;       scores(ca, sc);
.LBB0_1081:
	s_waitcnt vmcnt(0)
	v_mov_b64_e32 v[88:89], v[48:49]
	v_mov_b64_e32 v[86:87], v[46:47]
	v_mfma_f32_16x16x32_f16 v[54:57], v[50:53], v[38:41], 0
	v_mov_b32_e32 v0, v162
	v_add_u32_e32 v162, 4, v0
	v_cmp_gt_i32_e32 vcc, s68, v162
	v_mfma_f32_16x16x32_f16 v[46:49], v[86:89], v[38:41], 0
	v_mov_b32_e32 v127, v1
	v_cndmask_b32_e32 v0, v0, v162, vcc
	v_lshl_or_b32 v0, v0, 5, v157
	v_mfma_f32_16x16x32_f16 v[90:93], v[50:53], v[34:37], v[54:57]
	v_cmp_le_i32_e64 s[60:61], v160, v133
	v_mfma_f32_16x16x32_f16 v[54:57], v[86:89], v[34:37], v[46:49]
	s_nop 2
	v_mov_b64_e32 v[46:47], s[78:79]
	v_mad_i64_i32 v[48:49], s[2:3], v0, s5, v[46:47]
	v_lshl_add_u64 v[48:49], v[48:49], 0, v[126:127]
	v_or_b32_e32 v0, 16, v0
	v_add_co_u32_e32 v48, vcc, s23, v48
	v_mad_i64_i32 v[46:47], s[2:3], v0, s5, v[46:47]
	s_nop 0
	v_addc_co_u32_e32 v49, vcc, 0, v49, vcc
	v_lshl_add_u64 v[46:47], v[46:47], 0, v[126:127]
	v_add_co_u32_e32 v46, vcc, s23, v46
	v_mfma_f32_16x16x32_f16 v[94:97], v[50:53], v[26:29], 0
	s_nop 0
	v_addc_co_u32_e32 v47, vcc, 0, v47, vcc
	v_cmp_le_i32_e32 vcc, s68, v162
	v_mfma_f32_16x16x32_f16 v[98:101], v[50:53], v[2:5], 0
	v_mfma_f32_16x16x32_f16 v[102:105], v[50:53], v[6:9], 0
	v_mfma_f32_16x16x32_f16 v[106:109], v[50:53], v[10:13], 0
	v_mfma_f32_16x16x32_f16 v[110:113], v[50:53], v[14:17], 0
	v_mfma_f32_16x16x32_f16 v[114:117], v[50:53], v[18:21], 0
	v_mfma_f32_16x16x32_f16 v[118:121], v[50:53], v[22:25], 0
	v_mfma_f32_16x16x32_f16 v[122:125], v[50:53], v[30:33], 0
	global_load_dwordx4 v[50:53], v[48:49], off offset:2304
	s_nop 0
	global_load_dwordx4 v[46:49], v[46:47], off offset:2304
	v_mfma_f32_16x16x32_f16 v[58:61], v[86:89], v[26:29], 0
	v_mfma_f32_16x16x32_f16 v[62:65], v[86:89], v[2:5], 0
	v_mfma_f32_16x16x32_f16 v[66:69], v[86:89], v[6:9], 0
	v_mfma_f32_16x16x32_f16 v[70:73], v[86:89], v[10:13], 0
	v_mfma_f32_16x16x32_f16 v[74:77], v[86:89], v[14:17], 0
	v_mfma_f32_16x16x32_f16 v[78:81], v[86:89], v[18:21], 0
	v_mfma_f32_16x16x32_f16 v[82:85], v[86:89], v[22:25], 0
	v_mfma_f32_16x16x32_f16 v[86:89], v[86:89], v[30:33], 0
	s_xor_b64 s[14:15], s[46:47], exec
	s_cmp_lg_u64 s[14:15], 0
	s_cbranch_scc1 .Lcf_slow
; __device__ __forceinline__ void dsa_item(const KP& p, int b, int tile, char* smem) {
;     ...
; #pragma unroll
;       for (int q = 0; q < 8; ++q) {
;         const int key = kt * 32 + (q >> 2) * 16 + 4 * hq + (q & 3);
;         if (key <= myt) {
;           const uint32_t u32 = skey(sc[q]);
;           bool take, isc = false;
;           if (st0 == 0) take = (((unsigned long long)u32 << 16) | (unsigned long long)(8191 - key)) >= mytk;
;           else {
;             const uint32_t p16 = u32 >> 16;
;             take = p16 > (uint32_t)myp16;
;             isc = p16 == (uint32_t)myp16;
;           }
;           if (take) {
;             const int pos = atomicAdd(&cnt[mytok], 1);
;             if (pos < 256) sel[mytok * 256 + pos] = (unsigned short)key;
;           } else if (isc) {
;             const int pos = atomicAdd(&ccnt[mytok], 1);
;             if (pos < DSA_CAP) cand[mytok * 128 + pos] = ((unsigned long long)u32 << 16) | (unsigned long long)(8191 - key);
;           }
;         }
	s_mov_b64 s[2:3], exec
	s_and_b64 s[14:15], exec, vcc
	s_or_b64 s[96:97], s[14:15], s[96:97]
	v_sub_u32_e32 v166, v133, v160
	v_fma_f32 v194, |v94|, v128, v90
	v_fma_f32 v195, |v95|, v128, v91
	v_fma_f32 v196, |v96|, v128, v92
	v_fma_f32 v197, |v97|, v128, v93
	v_fma_f32 v194, |v98|, v130, v194
	v_fma_f32 v195, |v99|, v130, v195
	v_fma_f32 v196, |v100|, v130, v196
	v_fma_f32 v197, |v101|, v130, v197
	v_fma_f32 v194, |v102|, v132, v194
	v_fma_f32 v195, |v103|, v132, v195
	v_fma_f32 v196, |v104|, v132, v196
	v_fma_f32 v197, |v105|, v132, v197
	v_fma_f32 v194, |v106|, v134, v194
	v_fma_f32 v195, |v107|, v134, v195
	v_fma_f32 v196, |v108|, v134, v196
	v_fma_f32 v197, |v109|, v134, v197
	v_fma_f32 v194, |v110|, v136, v194
	v_fma_f32 v195, |v111|, v136, v195
	v_fma_f32 v196, |v112|, v136, v196
	v_fma_f32 v197, |v113|, v136, v197
	v_fma_f32 v194, |v114|, v138, v194
	v_fma_f32 v195, |v115|, v138, v195
	v_fma_f32 v196, |v116|, v138, v196
	v_fma_f32 v197, |v117|, v138, v197
	v_fma_f32 v194, |v118|, v140, v194
	v_fma_f32 v195, |v119|, v140, v195
	v_fma_f32 v196, |v120|, v140, v196
	v_fma_f32 v197, |v121|, v140, v197
	v_fma_f32 v194, |v122|, v142, v194
	v_fma_f32 v195, |v123|, v142, v195
	v_fma_f32 v196, |v124|, v142, v196
	v_fma_f32 v197, |v125|, v142, v197
	v_add_f32_e32 v194, 0, v194
	v_add_f32_e32 v195, 0, v195
	v_add_f32_e32 v196, 0, v196
	v_add_f32_e32 v197, 0, v197
	v_ashrrev_i32_e32 v198, 31, v194
	v_ashrrev_i32_e32 v199, 31, v195
	v_ashrrev_i32_e32 v200, 31, v196
	v_ashrrev_i32_e32 v201, 31, v197
	v_or_b32_e32 v198, 0x80000000, v198
	v_or_b32_e32 v199, 0x80000000, v199
	v_or_b32_e32 v200, 0x80000000, v200
	v_or_b32_e32 v201, 0x80000000, v201
	v_xor_b32_e32 v202, v194, v198
	v_xor_b32_e32 v203, v195, v199
	v_xor_b32_e32 v204, v196, v200
	v_xor_b32_e32 v205, v197, v201
	v_cmp_ge_i32_e64 s[60:61], v166, 0
	v_cmp_gt_u32_sdwa s[30:31], v202, v42 src0_sel:WORD_1 src1_sel:DWORD
	v_cmp_eq_u32_sdwa s[66:67], v202, v42 src0_sel:WORD_1 src1_sel:DWORD
	s_and_b64 s[30:31], s[30:31], s[60:61]
	s_and_b64 s[66:67], s[66:67], s[60:61]
	v_cndmask_b32_e64 v206, 0, 1, s[30:31]
	v_cndmask_b32_e64 v210, 0, 1, s[66:67]
	v_cmp_ge_i32_e64 s[60:61], v166, 1
	v_cmp_gt_u32_sdwa s[30:31], v203, v42 src0_sel:WORD_1 src1_sel:DWORD
	v_cmp_eq_u32_sdwa s[66:67], v203, v42 src0_sel:WORD_1 src1_sel:DWORD
	s_and_b64 s[30:31], s[30:31], s[60:61]
	s_and_b64 s[66:67], s[66:67], s[60:61]
	v_cndmask_b32_e64 v207, 0, 1, s[30:31]
	v_cndmask_b32_e64 v211, 0, 1, s[66:67]
	v_cmp_ge_i32_e64 s[60:61], v166, 2
	v_cmp_gt_u32_sdwa s[30:31], v204, v42 src0_sel:WORD_1 src1_sel:DWORD
	v_cmp_eq_u32_sdwa s[66:67], v204, v42 src0_sel:WORD_1 src1_sel:DWORD
	s_and_b64 s[30:31], s[30:31], s[60:61]
	s_and_b64 s[66:67], s[66:67], s[60:61]
	v_cndmask_b32_e64 v208, 0, 1, s[30:31]
	v_cndmask_b32_e64 v212, 0, 1, s[66:67]
	v_cmp_ge_i32_e64 s[60:61], v166, 3
	v_cmp_gt_u32_sdwa s[30:31], v205, v42 src0_sel:WORD_1 src1_sel:DWORD
	v_cmp_eq_u32_sdwa s[66:67], v205, v42 src0_sel:WORD_1 src1_sel:DWORD
	s_and_b64 s[30:31], s[30:31], s[60:61]
	s_and_b64 s[66:67], s[66:67], s[60:61]
	v_cndmask_b32_e64 v209, 0, 1, s[30:31]
	v_cndmask_b32_e64 v213, 0, 1, s[66:67]
	v_cmp_ne_u32_e32 vcc, 0, v206
	s_mov_b64 exec, vcc
	ds_add_rtn_u32 v214, v145, v206 offset:41344
	s_mov_b64 exec, s[2:3]
	v_cmp_ne_u32_e32 vcc, 0, v207
	s_mov_b64 exec, vcc
	ds_add_rtn_u32 v215, v145, v207 offset:41344
	s_mov_b64 exec, s[2:3]
	v_cmp_ne_u32_e32 vcc, 0, v208
	s_mov_b64 exec, vcc
	ds_add_rtn_u32 v216, v145, v208 offset:41344
	s_mov_b64 exec, s[2:3]
	v_cmp_ne_u32_e32 vcc, 0, v209
	s_mov_b64 exec, vcc
	ds_add_rtn_u32 v217, v145, v209 offset:41344
	s_mov_b64 exec, s[2:3]
	v_cmp_ne_u32_e32 vcc, 0, v210
	s_mov_b64 exec, vcc
	ds_add_rtn_u32 v218, v145, v210 offset:41408
	s_mov_b64 exec, s[2:3]
	v_cmp_ne_u32_e32 vcc, 0, v211
	s_mov_b64 exec, vcc
	ds_add_rtn_u32 v219, v145, v211 offset:41408
	s_mov_b64 exec, s[2:3]
	v_cmp_ne_u32_e32 vcc, 0, v212
	s_mov_b64 exec, vcc
	ds_add_rtn_u32 v220, v145, v212 offset:41408
	s_mov_b64 exec, s[2:3]
	v_cmp_ne_u32_e32 vcc, 0, v213
	s_mov_b64 exec, vcc
	ds_add_rtn_u32 v221, v145, v213 offset:41408
	s_mov_b64 exec, s[2:3]
	v_lshlrev_b32_e32 v198, 8, v206
	v_lshlrev_b32_e32 v199, 8, v207
	v_lshlrev_b32_e32 v200, 8, v208
	v_lshlrev_b32_e32 v201, 8, v209
	v_lshlrev_b32_e32 v194, 7, v210
	v_lshlrev_b32_e32 v195, 7, v211
	v_lshlrev_b32_e32 v196, 7, v212
	v_lshlrev_b32_e32 v197, 7, v213
	s_waitcnt lgkmcnt(0)
	v_cmp_lt_u32_e32 vcc, v214, v198
	v_lshl_add_u32 v167, v214, 1, v43
	s_mov_b64 exec, vcc
	ds_write_b16 v167, v160 offset:32768
	s_mov_b64 exec, s[2:3]
	v_cmp_lt_u32_e32 vcc, v215, v199
	v_lshl_add_u32 v167, v215, 1, v43
	v_add_u32_e32 v168, 1, v160
	s_mov_b64 exec, vcc
	ds_write_b16 v167, v168 offset:32768
	s_mov_b64 exec, s[2:3]
	v_cmp_lt_u32_e32 vcc, v216, v200
	v_lshl_add_u32 v167, v216, 1, v43
	v_add_u32_e32 v168, 2, v160
	s_mov_b64 exec, vcc
	ds_write_b16 v167, v168 offset:32768
	s_mov_b64 exec, s[2:3]
	v_cmp_lt_u32_e32 vcc, v217, v201
	v_lshl_add_u32 v167, v217, 1, v43
	v_add_u32_e32 v168, 3, v160
	s_mov_b64 exec, vcc
	ds_write_b16 v167, v168 offset:32768
	s_mov_b64 exec, s[2:3]
	v_cmp_lt_u32_e32 vcc, v218, v194
	s_mov_b64 exec, vcc
	s_cbranch_execz .Lcf_nc00
	v_lshrrev_b32_e32 v223, 16, v202
	v_mov_b32_e32 v169, v161
	v_lshl_or_b32 v222, v202, 16, v169
	v_lshl_add_u32 v167, v218, 3, v147
	ds_write_b64 v167, v[222:223] offset:16384

; __device__ __forceinline__ void dsa_item(const KP& p, int b, int tile, char* smem) {
;     ...
; #pragma unroll
;       for (int q = 0; q < 8; ++q) {
;         const int key = kt * 32 + (q >> 2) * 16 + 4 * hq + (q & 3);
;         if (key <= myt) {
;           const uint32_t u32 = skey(sc[q]);
;           bool take, isc = false;
;           if (st0 == 0) take = (((unsigned long long)u32 << 16) | (unsigned long long)(8191 - key)) >= mytk;
;           else {
;             const uint32_t p16 = u32 >> 16;
;             take = p16 > (uint32_t)myp16;
;             isc = p16 == (uint32_t)myp16;
;           }
;           if (take) {
;             const int pos = atomicAdd(&cnt[mytok], 1);
;             if (pos < 256) sel[mytok * 256 + pos] = (unsigned short)key;
;           } else if (isc) {
;             const int pos = atomicAdd(&ccnt[mytok], 1);
;             if (pos < DSA_CAP) cand[mytok * 128 + pos] = ((unsigned long long)u32 << 16) | (unsigned long long)(8191 - key);
;           }
;         }
.Lcf_nc03:
	s_mov_b64 exec, s[2:3]
	v_fma_f32 v194, |v58|, v128, v54
	v_fma_f32 v195, |v59|, v128, v55
	v_fma_f32 v196, |v60|, v128, v56
	v_fma_f32 v197, |v61|, v128, v57
	v_fma_f32 v194, |v62|, v130, v194
	v_fma_f32 v195, |v63|, v130, v195
	v_fma_f32 v196, |v64|, v130, v196
	v_fma_f32 v197, |v65|, v130, v197
	v_fma_f32 v194, |v66|, v132, v194
	v_fma_f32 v195, |v67|, v132, v195
	v_fma_f32 v196, |v68|, v132, v196
	v_fma_f32 v197, |v69|, v132, v197
	v_fma_f32 v194, |v70|, v134, v194
	v_fma_f32 v195, |v71|, v134, v195
	v_fma_f32 v196, |v72|, v134, v196
	v_fma_f32 v197, |v73|, v134, v197
	v_fma_f32 v194, |v74|, v136, v194
	v_fma_f32 v195, |v75|, v136, v195
	v_fma_f32 v196, |v76|, v136, v196
	v_fma_f32 v197, |v77|, v136, v197
	v_fma_f32 v194, |v78|, v138, v194
	v_fma_f32 v195, |v79|, v138, v195
	v_fma_f32 v196, |v80|, v138, v196
	v_fma_f32 v197, |v81|, v138, v197
	v_fma_f32 v194, |v82|, v140, v194
	v_fma_f32 v195, |v83|, v140, v195
	v_fma_f32 v196, |v84|, v140, v196
	v_fma_f32 v197, |v85|, v140, v197
	v_fma_f32 v194, |v86|, v142, v194
	v_fma_f32 v195, |v87|, v142, v195
	v_fma_f32 v196, |v88|, v142, v196
	v_fma_f32 v197, |v89|, v142, v197
	v_add_f32_e32 v194, 0, v194
	v_add_f32_e32 v195, 0, v195
	v_add_f32_e32 v196, 0, v196
	v_add_f32_e32 v197, 0, v197
	v_ashrrev_i32_e32 v198, 31, v194
	v_ashrrev_i32_e32 v199, 31, v195
	v_ashrrev_i32_e32 v200, 31, v196
	v_ashrrev_i32_e32 v201, 31, v197
	v_or_b32_e32 v198, 0x80000000, v198
	v_or_b32_e32 v199, 0x80000000, v199
	v_or_b32_e32 v200, 0x80000000, v200
	v_or_b32_e32 v201, 0x80000000, v201
	v_xor_b32_e32 v202, v194, v198
	v_xor_b32_e32 v203, v195, v199
	v_xor_b32_e32 v204, v196, v200
	v_xor_b32_e32 v205, v197, v201
	v_cmp_ge_i32_e64 s[60:61], v166, 16
	v_cmp_gt_u32_sdwa s[30:31], v202, v42 src0_sel:WORD_1 src1_sel:DWORD
	v_cmp_eq_u32_sdwa s[66:67], v202, v42 src0_sel:WORD_1 src1_sel:DWORD
	s_and_b64 s[30:31], s[30:31], s[60:61]
	s_and_b64 s[66:67], s[66:67], s[60:61]
	v_cndmask_b32_e64 v206, 0, 1, s[30:31]
	v_cndmask_b32_e64 v210, 0, 1, s[66:67]
	v_cmp_ge_i32_e64 s[60:61], v166, 17
	v_cmp_gt_u32_sdwa s[30:31], v203, v42 src0_sel:WORD_1 src1_sel:DWORD
	v_cmp_eq_u32_sdwa s[66:67], v203, v42 src0_sel:WORD_1 src1_sel:DWORD
	s_and_b64 s[30:31], s[30:31], s[60:61]
	s_and_b64 s[66:67], s[66:67], s[60:61]
	v_cndmask_b32_e64 v207, 0, 1, s[30:31]
	v_cndmask_b32_e64 v211, 0, 1, s[66:67]
	v_cmp_ge_i32_e64 s[60:61], v166, 18
	v_cmp_gt_u32_sdwa s[30:31], v204, v42 src0_sel:WORD_1 src1_sel:DWORD
	v_cmp_eq_u32_sdwa s[66:67], v204, v42 src0_sel:WORD_1 src1_sel:DWORD
	s_and_b64 s[30:31], s[30:31], s[60:61]
	s_and_b64 s[66:67], s[66:67], s[60:61]
	v_cndmask_b32_e64 v208, 0, 1, s[30:31]
	v_cndmask_b32_e64 v212, 0, 1, s[66:67]
	v_cmp_ge_i32_e64 s[60:61], v166, 19
	v_cmp_gt_u32_sdwa s[30:31], v205, v42 src0_sel:WORD_1 src1_sel:DWORD
	v_cmp_eq_u32_sdwa s[66:67], v205, v42 src0_sel:WORD_1 src1_sel:DWORD
	s_and_b64 s[30:31], s[30:31], s[60:61]
	s_and_b64 s[66:67], s[66:67], s[60:61]
	v_cndmask_b32_e64 v209, 0, 1, s[30:31]
	v_cndmask_b32_e64 v213, 0, 1, s[66:67]
	v_cmp_ne_u32_e32 vcc, 0, v206
	s_mov_b64 exec, vcc
	ds_add_rtn_u32 v214, v145, v206 offset:41344
	s_mov_b64 exec, s[2:3]
	v_cmp_ne_u32_e32 vcc, 0, v207
	s_mov_b64 exec, vcc
	ds_add_rtn_u32 v215, v145, v207 offset:41344
	s_mov_b64 exec, s[2:3]
	v_cmp_ne_u32_e32 vcc, 0, v208
	s_mov_b64 exec, vcc
	ds_add_rtn_u32 v216, v145, v208 offset:41344
	s_mov_b64 exec, s[2:3]
	v_cmp_ne_u32_e32 vcc, 0, v209
	s_mov_b64 exec, vcc
	ds_add_rtn_u32 v217, v145, v209 offset:41344
	s_mov_b64 exec, s[2:3]
	v_cmp_ne_u32_e32 vcc, 0, v210
	s_mov_b64 exec, vcc
	ds_add_rtn_u32 v218, v145, v210 offset:41408
	s_mov_b64 exec, s[2:3]
	v_cmp_ne_u32_e32 vcc, 0, v211
	s_mov_b64 exec, vcc
	ds_add_rtn_u32 v219, v145, v211 offset:41408
	s_mov_b64 exec, s[2:3]
	v_cmp_ne_u32_e32 vcc, 0, v212
	s_mov_b64 exec, vcc
	ds_add_rtn_u32 v220, v145, v212 offset:41408
	s_mov_b64 exec, s[2:3]
	v_cmp_ne_u32_e32 vcc, 0, v213
	s_mov_b64 exec, vcc
	ds_add_rtn_u32 v221, v145, v213 offset:41408
	s_mov_b64 exec, s[2:3]
	v_lshlrev_b32_e32 v198, 8, v206
	v_lshlrev_b32_e32 v199, 8, v207
	v_lshlrev_b32_e32 v200, 8, v208
	v_lshlrev_b32_e32 v201, 8, v209
	v_lshlrev_b32_e32 v194, 7, v210
	v_lshlrev_b32_e32 v195, 7, v211
	v_lshlrev_b32_e32 v196, 7, v212
	v_lshlrev_b32_e32 v197, 7, v213
	s_waitcnt lgkmcnt(0)
	v_cmp_lt_u32_e32 vcc, v214, v198
	v_lshl_add_u32 v167, v214, 1, v43
	v_add_u32_e32 v168, 16, v160
	s_mov_b64 exec, vcc
	ds_write_b16 v167, v168 offset:32768
	s_mov_b64 exec, s[2:3]
	v_cmp_lt_u32_e32 vcc, v215, v199
	v_lshl_add_u32 v167, v215, 1, v43
	v_add_u32_e32 v168, 17, v160
	s_mov_b64 exec, vcc
	ds_write_b16 v167, v168 offset:32768
	s_mov_b64 exec, s[2:3]
	v_cmp_lt_u32_e32 vcc, v216, v200
	v_lshl_add_u32 v167, v216, 1, v43
	v_add_u32_e32 v168, 18, v160
	s_mov_b64 exec, vcc
	ds_write_b16 v167, v168 offset:32768
	s_mov_b64 exec, s[2:3]
	v_cmp_lt_u32_e32 vcc, v217, v201
	v_lshl_add_u32 v167, v217, 1, v43
	v_add_u32_e32 v168, 19, v160
	s_mov_b64 exec, vcc
	ds_write_b16 v167, v168 offset:32768
	s_mov_b64 exec, s[2:3]
	v_cmp_lt_u32_e32 vcc, v218, v194
	s_mov_b64 exec, vcc
	s_cbranch_execz .Lcf_nc10
	v_lshrrev_b32_e32 v223, 16, v202
	v_subrev_u32_e32 v169, 16, v161
	v_lshl_or_b32 v222, v202, 16, v169
	v_lshl_add_u32 v167, v218, 3, v147
	ds_write_b64 v167, v[222:223] offset:16384
